# mixer-B fast loop: next-tile LDS-DMA issue moved from the loop head (right after the tile barrier) into the QK MFMA shadow of each wave half
# baseline (speedup 1.0000x reference)
; template <int MODE, int NQ, int TS, bool FAST = false> ...
;     ...
;   auto QK = [&](int slot) {
;     const char* kb_ = lds + slot * 16384;
; #pragma unroll
;     for (int nq = 0; nq < NQ; ++nq)
; #pragma unroll
;       for (int r = 0; r < 16; ++r) { s[nq][0][r] = 0.f; s[nq][1][r] = 0.f; }
; #pragma unroll
;     for (int ks = 0; ks < 4; ++ks) {
;       const bf16x8 k0 = *(const bf16x8*)(kb_ + kfo4[ks]), k1 = *(const bf16x8*)(kb_ + kfo4[ks] + 4096);
; #pragma unroll
;       for (int nq = 0; nq < NQ; ++nq) { s[nq][0] = MFMA32(k0, qf[nq][ks], s[nq][0]); s[nq][1] = MFMA32(k1, qf[nq][ks], s[nq][1]); }
;     }
;     ...
;       for (int r = 0; r < 16; ++r) {
;         float pa, pb;
;         if (MODE == 1) {
;           if (FAST) { pa = __builtin_amdgcn_exp2f(s0[r]); pb = __builtin_amdgcn_exp2f(s1[r]); }
;           else { pa = __builtin_amdgcn_exp2f(s0[r] - mn); pb = __builtin_amdgcn_exp2f(s1[r] - mn); }
;         }
;         else { pa = __builtin_amdgcn_exp2f(s0[r] - mn); pb = __builtin_amdgcn_exp2f(s1[r] - mn); }
;         s0[r] = pa; s1[r] = pb; ls += pa + pb;
;       }
;       l[nq] += ls;
; #pragma unroll
;       for (int ks = 0; ks < 4; ++ks) {
;         uint4 t4;
;         const int rb = 8 * (ks & 1);
;         if (ks < 2) { t4.x = pack2(s0[rb], s0[rb + 1]); t4.y = pack2(s0[rb + 2], s0[rb + 3]); t4.z = pack2(s0[rb + 4], s0[rb + 5]); t4.w = pack2(s0[rb + 6], s0[rb + 7]); }
;         else { t4.x = pack2(s1[rb], s1[rb + 1]); t4.y = pack2(s1[rb + 2], s1[rb + 3]); t4.z = pack2(s1[rb + 4], s1[rb + 5]); t4.w = pack2(s1[rb + 6], s1[rb + 7]); }
;         pf[nq][ks] = __builtin_bit_cast(bf16x8, t4);
;       }
;     }
;   };
;   auto PV = [&](int slot) {
;     const char* vb_ = lds + slot * 16384 + vfo;
; #pragma unroll
;     for (int ks = 0; ks < 4; ++ks) {
;       const s16x4 a0 = vtr(vb_ + ks * 1024), a1 = vtr(vb_ + ks * 1024 + 512);
;       const s16x4 b0 = vtr(vb_ + 4096 + ks * 1024), b1 = vtr(vb_ + 4096 + ks * 1024 + 512);
;       const bf16x8 v0 = __builtin_shufflevector(a0, a1, 0, 1, 2, 3, 4, 5, 6, 7);
;       const bf16x8 v1 = __builtin_shufflevector(b0, b1, 0, 1, 2, 3, 4, 5, 6, 7);
; #pragma unroll
;       for (int nq = 0; nq < NQ; ++nq) { o[nq][0] = MFMA32(v0, pf[nq][ks], o[nq][0]); o[nq][1] = MFMA32(v1, pf[nq][ks], o[nq][1]); }
;     }
;   };
;   int slot = 0, sp = 0;
;   for (int kt = kt0; kt < kt1; ++kt) {
.LBB0_436:
	s_mov_b32 s8, s12
	s_and_saveexec_b64 s[12:13], s[38:39]
	s_xor_b64 s[26:27], exec, s[12:13]
	s_cbranch_execz .LBB0_438
	s_lshl_b32 s12, s8, 14
	v_or_b32_e32 v70, s12, v183
	ds_read_b128 v[66:69], v70
	ds_read_b128 v[82:85], v70 offset:4096
	v_or_b32_e32 v180, s12, v184
	ds_read_b128 v[176:179], v180
	ds_read_b128 v[188:191], v180 offset:4096
	v_or_b32_e32 v180, s12, v186
	s_waitcnt lgkmcnt(0)
	v_mfma_f32_32x32x16_bf16 v[98:113], v[66:69], v[130:133], 0
	v_mfma_f32_32x32x16_bf16 v[114:129], v[82:85], v[130:133], 0
	v_mfma_f32_32x32x16_bf16 v[82:97], v[82:85], v[146:149], 0
	v_mfma_f32_32x32x16_bf16 v[66:81], v[66:69], v[146:149], 0
	v_mfma_f32_32x32x16_bf16 v[82:97], v[188:191], v[150:153], v[82:97]
	v_mfma_f32_32x32x16_bf16 v[98:113], v[176:179], v[134:137], v[98:113]
	v_mfma_f32_32x32x16_bf16 v[114:129], v[188:191], v[134:137], v[114:129]
	v_mfma_f32_32x32x16_bf16 v[66:81], v[176:179], v[150:153], v[66:81]
	ds_read_b128 v[176:179], v180
	ds_read_b128 v[188:191], v180 offset:4096
	v_or_b32_e32 v180, s12, v187
	s_add_i32 s98, s7, 4
	s_min_i32 s98, s98, s6
	s_cmp_gt_i32 s8, 1
	s_cselect_b32 s99, -2, 4
	s_add_i32 s99, s99, s8
	s_lshl_b32 s99, s99, 14
	s_add_i32 s99, s4, s99
	v_mad_i64_i32 v[250:251], s[100:101], s98, v237, v[172:173]
	s_mov_b32 m0, s99
	s_nop 0
	global_load_lds_dwordx4 v[250:251], off
	v_mad_i64_i32 v[250:251], s[100:101], s98, v237, v[174:175]
	s_add_i32 m0, s99, 0x2000
	s_nop 0
	global_load_lds_dwordx4 v[250:251], off
	s_waitcnt lgkmcnt(0)
	v_mfma_f32_32x32x16_bf16 v[82:97], v[188:191], v[154:157], v[82:97]
	v_mfma_f32_32x32x16_bf16 v[98:113], v[176:179], v[138:141], v[98:113]
	v_mfma_f32_32x32x16_bf16 v[114:129], v[188:191], v[138:141], v[114:129]
	v_mfma_f32_32x32x16_bf16 v[66:81], v[176:179], v[154:157], v[66:81]
	ds_read_b128 v[176:179], v180
	ds_read_b128 v[188:191], v180 offset:4096
	s_waitcnt lgkmcnt(0)
	v_mfma_f32_32x32x16_bf16 v[82:97], v[188:191], v[158:161], v[82:97]
	v_mfma_f32_32x32x16_bf16 v[98:113], v[176:179], v[142:145], v[98:113]
	s_nop 10
	v_exp_f32_e32 v214, v92
	v_or_b32_e32 v92, s12, v185
	v_exp_f32_e32 v196, v86
	v_exp_f32_e32 v202, v88
	v_exp_f32_e32 v208, v90
	v_exp_f32_e32 v220, v94
	v_exp_f32_e32 v242, v96
	v_mfma_f32_32x32x16_bf16 v[114:129], v[188:191], v[142:145], v[114:129]
	v_exp_f32_e32 v181, v99
	v_exp_f32_e32 v189, v100
	v_exp_f32_e32 v193, v101
	v_exp_f32_e32 v195, v102
	v_exp_f32_e32 v199, v103
	v_exp_f32_e32 v201, v104
	v_exp_f32_e32 v205, v105
	v_mfma_f32_32x32x16_bf16 v[66:81], v[176:179], v[158:161], v[66:81]
	v_exp_f32_e32 v177, v98
	s_nop 2
	v_exp_f32_e32 v191, v116
	v_exp_f32_e32 v197, v118
	v_exp_f32_e32 v203, v120
	v_exp_f32_e32 v209, v122
	v_exp_f32_e32 v190, v84
	v_exp_f32_e32 v116, v85
	s_nop 1
	v_exp_f32_e32 v176, v66
	v_exp_f32_e32 v180, v67
	v_exp_f32_e32 v188, v68
	v_exp_f32_e32 v192, v69
	v_exp_f32_e32 v194, v70
	v_exp_f32_e32 v198, v71
	v_exp_f32_e32 v118, v87
	v_exp_f32_e32 v200, v72
	v_exp_f32_e32 v204, v73
	v_exp_f32_e32 v120, v89
	v_exp_f32_e32 v122, v91
	ds_read_b64_tr_b16 v[84:85], v92 offset:8192
	ds_read_b64_tr_b16 v[86:87], v92 offset:8704
	ds_read_b64_tr_b16 v[88:89], v92 offset:12288
	ds_read_b64_tr_b16 v[90:91], v92 offset:12800
	v_exp_f32_e32 v219, v110
	v_exp_f32_e32 v227, v111
	v_exp_f32_e32 v229, v112
	v_exp_f32_e32 v245, v113
	v_cvt_pk_bf16_f32 v110, v177, v181
	v_cvt_pk_bf16_f32 v111, v189, v193
	v_cvt_pk_bf16_f32 v112, v195, v199
	v_cvt_pk_bf16_f32 v113, v201, v205
	v_exp_f32_e32 v218, v78
	v_exp_f32_e32 v226, v79
	v_exp_f32_e32 v228, v80
	v_exp_f32_e32 v244, v81
	v_cvt_pk_bf16_f32 v78, v176, v180
	v_cvt_pk_bf16_f32 v79, v188, v192
	v_cvt_pk_bf16_f32 v80, v194, v198
	v_cvt_pk_bf16_f32 v81, v200, v204
	s_waitcnt lgkmcnt(0)
; #define MFMA32(a, b, c) __builtin_amdgcn_mfma_f32_32x32x16_bf16((a), (b), (c), 0, 0, 0)
; DI unsigned pack2(float lo, float hi) { f32x2_t v = {lo, hi}; return __builtin_bit_cast(unsigned, __builtin_convertvector(v, bf16x2_t)); }
; DI s16x4 vtr(const char* p) { return __builtin_amdgcn_ds_read_tr16_b64_v4i16((lds_s16x4_ptr)p); }
; template <int MODE, int NQ, int TS, bool FAST = false> ...
;     ...
;       float ls = 0.f;
; #pragma unroll
;       for (int r = 0; r < 16; ++r) {
;         float pa, pb;
;         if (MODE == 1) {
;           if (FAST) { pa = __builtin_amdgcn_exp2f(s0[r]); pb = __builtin_amdgcn_exp2f(s1[r]); }
;           else { pa = __builtin_amdgcn_exp2f(s0[r] - mn); pb = __builtin_amdgcn_exp2f(s1[r] - mn); }
;         }
;         else { pa = __builtin_amdgcn_exp2f(s0[r] - mn); pb = __builtin_amdgcn_exp2f(s1[r] - mn); }
;         s0[r] = pa; s1[r] = pb; ls += pa + pb;
;       }
;       l[nq] += ls;
; #pragma unroll
;       for (int ks = 0; ks < 4; ++ks) {
;         uint4 t4;
;         const int rb = 8 * (ks & 1);
;         if (ks < 2) { t4.x = pack2(s0[rb], s0[rb + 1]); t4.y = pack2(s0[rb + 2], s0[rb + 3]); t4.z = pack2(s0[rb + 4], s0[rb + 5]); t4.w = pack2(s0[rb + 6], s0[rb + 7]); }
;         else { t4.x = pack2(s1[rb], s1[rb + 1]); t4.y = pack2(s1[rb + 2], s1[rb + 3]); t4.z = pack2(s1[rb + 4], s1[rb + 5]); t4.w = pack2(s1[rb + 6], s1[rb + 7]); }
;         pf[nq][ks] = __builtin_bit_cast(bf16x8, t4);
;       }
;     }
;   };
;   auto PV = [&](int slot) {
;     const char* vb_ = lds + slot * 16384 + vfo;
; #pragma unroll
;     for (int ks = 0; ks < 4; ++ks) {
;       const s16x4 a0 = vtr(vb_ + ks * 1024), a1 = vtr(vb_ + ks * 1024 + 512);
;       const s16x4 b0 = vtr(vb_ + 4096 + ks * 1024), b1 = vtr(vb_ + 4096 + ks * 1024 + 512);
;       const bf16x8 v0 = __builtin_shufflevector(a0, a1, 0, 1, 2, 3, 4, 5, 6, 7);
;       const bf16x8 v1 = __builtin_shufflevector(b0, b1, 0, 1, 2, 3, 4, 5, 6, 7);
; #pragma unroll
;       for (int nq = 0; nq < NQ; ++nq) { o[nq][0] = MFMA32(v0, pf[nq][ks], o[nq][0]); o[nq][1] = MFMA32(v1, pf[nq][ks], o[nq][1]); }
;     }
	v_mfma_f32_32x32x16_bf16 v[50:65], v[84:87], v[110:113], v[50:65]
	v_exp_f32_e32 v179, v114
	v_exp_f32_e32 v207, v106
	v_exp_f32_e32 v211, v107
	v_exp_f32_e32 v213, v108
	v_exp_f32_e32 v217, v109
	v_exp_f32_e32 v178, v82
	v_exp_f32_e32 v206, v74
	v_mfma_f32_32x32x16_bf16 v[34:49], v[88:91], v[110:113], v[34:49]
	v_exp_f32_e32 v210, v75
	v_exp_f32_e32 v212, v76
	v_exp_f32_e32 v216, v77
	v_exp_f32_e32 v115, v115
	v_exp_f32_e32 v114, v83
	v_exp_f32_e32 v117, v117
	v_cvt_pk_bf16_f32 v106, v207, v211
	v_mfma_f32_32x32x16_bf16 v[18:33], v[84:87], v[78:81], v[18:33]
	v_cvt_pk_bf16_f32 v107, v213, v217
	v_cvt_pk_bf16_f32 v108, v219, v227
	v_cvt_pk_bf16_f32 v109, v229, v245
	v_add_f32_e64 v66, v176, v178
	v_add_f32_e64 v67, v177, v179
	v_cvt_pk_bf16_f32 v74, v206, v210
	v_cvt_pk_bf16_f32 v75, v212, v216
	v_cvt_pk_bf16_f32 v76, v218, v226
	v_mfma_f32_32x32x16_bf16 v[2:17], v[88:91], v[78:81], v[2:17]
	ds_read_b64_tr_b16 v[84:85], v92 offset:9216
	ds_read_b64_tr_b16 v[86:87], v92 offset:9728
	ds_read_b64_tr_b16 v[88:89], v92 offset:13312
	ds_read_b64_tr_b16 v[90:91], v92 offset:13824
	v_cvt_pk_bf16_f32 v77, v228, v244
	v_exp_f32_e32 v119, v119
	v_pk_add_f32 v[66:67], v[66:67], 0 op_sel_hi:[1,0]
	v_pk_add_f32 v[68:69], v[180:181], v[114:115]
	v_exp_f32_e32 v121, v121
	v_pk_add_f32 v[66:67], v[68:69], v[66:67]
	s_waitcnt lgkmcnt(0)
	v_mfma_f32_32x32x16_bf16 v[50:65], v[84:87], v[106:109], v[50:65]
	v_add_f32_e64 v68, v188, v190
	v_add_f32_e64 v69, v189, v191
	v_exp_f32_e32 v123, v123
	v_pk_add_f32 v[66:67], v[68:69], v[66:67]
	v_pk_add_f32 v[68:69], v[192:193], v[116:117]
	v_exp_f32_e32 v215, v124
	v_pk_add_f32 v[66:67], v[68:69], v[66:67]
	v_pk_add_f32 v[68:69], v[194:195], v[196:197]
	v_mfma_f32_32x32x16_bf16 v[34:49], v[88:91], v[106:109], v[34:49]
	v_add_f32_e64 v66, v68, v66
	v_add_f32_e64 v67, v69, v67
	v_add_f32_e64 v68, v198, v118
	v_add_f32_e64 v69, v199, v119
	v_exp_f32_e32 v125, v125
	v_pk_add_f32 v[66:67], v[68:69], v[66:67]
	v_pk_add_f32 v[68:69], v[200:201], v[202:203]
	v_exp_f32_e32 v124, v93
	v_pk_add_f32 v[66:67], v[68:69], v[66:67]
	v_mfma_f32_32x32x16_bf16 v[18:33], v[84:87], v[74:77], v[18:33]
	v_add_f32_e64 v68, v204, v120
	v_add_f32_e64 v69, v205, v121
	v_exp_f32_e32 v221, v126
	v_cvt_pk_bf16_f32 v102, v179, v115
	v_cvt_pk_bf16_f32 v103, v191, v117
	v_cvt_pk_bf16_f32 v104, v197, v119
	v_cvt_pk_bf16_f32 v105, v203, v121
	v_pk_add_f32 v[66:67], v[68:69], v[66:67]
	v_mfma_f32_32x32x16_bf16 v[2:17], v[88:91], v[74:77], v[2:17]
	ds_read_b64_tr_b16 v[84:85], v92 offset:10240
	ds_read_b64_tr_b16 v[86:87], v92 offset:10752
	ds_read_b64_tr_b16 v[88:89], v92 offset:14336
	ds_read_b64_tr_b16 v[90:91], v92 offset:14848
	v_add_f32_e64 v68, v206, v208
	v_add_f32_e64 v69, v207, v209
	v_cvt_pk_bf16_f32 v70, v178, v114
	v_cvt_pk_bf16_f32 v71, v190, v116
	v_cvt_pk_bf16_f32 v72, v196, v118
	v_cvt_pk_bf16_f32 v73, v202, v120
	v_exp_f32_e32 v127, v127
	v_exp_f32_e32 v126, v95
	v_pk_add_f32 v[66:67], v[68:69], v[66:67]
	v_pk_add_f32 v[68:69], v[210:211], v[122:123]
	s_waitcnt lgkmcnt(0)
	v_mfma_f32_32x32x16_bf16 v[50:65], v[84:87], v[102:105], v[50:65]
	v_exp_f32_e32 v243, v128
	v_pk_add_f32 v[66:67], v[68:69], v[66:67]
	v_pk_add_f32 v[68:69], v[212:213], v[214:215]
	v_exp_f32_e32 v129, v129
	v_exp_f32_e32 v128, v97
	v_pk_add_f32 v[66:67], v[68:69], v[66:67]
	v_pk_add_f32 v[68:69], v[216:217], v[124:125]
	v_mfma_f32_32x32x16_bf16 v[34:49], v[88:91], v[102:105], v[34:49]
	v_add_f32_e64 v66, v68, v66
	v_add_f32_e64 v67, v69, v67
	v_add_f32_e64 v68, v218, v220
	v_add_f32_e64 v69, v219, v221
	v_cvt_pk_bf16_f32 v98, v209, v123
	v_pk_add_f32 v[66:67], v[68:69], v[66:67]
	v_pk_add_f32 v[68:69], v[226:227], v[126:127]
	v_cvt_pk_bf16_f32 v99, v215, v125
	v_pk_add_f32 v[66:67], v[68:69], v[66:67]
	v_mfma_f32_32x32x16_bf16 v[18:33], v[84:87], v[70:73], v[18:33]
	v_add_f32_e64 v68, v228, v242
	v_add_f32_e64 v69, v229, v243
	v_cvt_pk_bf16_f32 v100, v221, v127
	v_add_f32_e64 v66, v68, v66
	v_add_f32_e64 v67, v69, v67
	v_pk_add_f32 v[68:69], v[244:245], v[128:129]
	v_cvt_pk_bf16_f32 v101, v243, v129
	v_pk_add_f32 v[82:83], v[68:69], v[66:67]
	v_cvt_pk_bf16_f32 v66, v208, v122
	v_mfma_f32_32x32x16_bf16 v[2:17], v[88:91], v[70:73], v[2:17]
	ds_read_b64_tr_b16 v[84:85], v92 offset:11264
	ds_read_b64_tr_b16 v[86:87], v92 offset:11776
	ds_read_b64_tr_b16 v[88:89], v92 offset:15360
	ds_read_b64_tr_b16 v[90:91], v92 offset:15872
	v_cvt_pk_bf16_f32 v67, v214, v124
	v_cvt_pk_bf16_f32 v68, v220, v126
	v_cvt_pk_bf16_f32 v69, v242, v128
	s_waitcnt lgkmcnt(0)
	v_mfma_f32_32x32x16_bf16 v[50:65], v[84:87], v[98:101], v[50:65]
	v_mfma_f32_32x32x16_bf16 v[34:49], v[88:91], v[98:101], v[34:49]
	v_mfma_f32_32x32x16_bf16 v[18:33], v[84:87], v[66:69], v[18:33]
	v_mfma_f32_32x32x16_bf16 v[2:17], v[88:91], v[66:69], v[2:17]

; #define MFMA32(a, b, c) __builtin_amdgcn_mfma_f32_32x32x16_bf16((a), (b), (c), 0, 0, 0)
; DI unsigned pack2(float lo, float hi) { f32x2_t v = {lo, hi}; return __builtin_bit_cast(unsigned, __builtin_convertvector(v, bf16x2_t)); }
; template <int MODE, int NQ, int TS, bool FAST = false> ...
;     ...
;   auto QK = [&](int slot) {
;     const char* kb_ = lds + slot * 16384;
; #pragma unroll
;     for (int nq = 0; nq < NQ; ++nq)
; #pragma unroll
;       for (int r = 0; r < 16; ++r) { s[nq][0][r] = 0.f; s[nq][1][r] = 0.f; }
; #pragma unroll
;     for (int ks = 0; ks < 4; ++ks) {
;       const bf16x8 k0 = *(const bf16x8*)(kb_ + kfo4[ks]), k1 = *(const bf16x8*)(kb_ + kfo4[ks] + 4096);
; #pragma unroll
;       for (int nq = 0; nq < NQ; ++nq) { s[nq][0] = MFMA32(k0, qf[nq][ks], s[nq][0]); s[nq][1] = MFMA32(k1, qf[nq][ks], s[nq][1]); }
;     }
;     ...
;       float ls = 0.f;
; #pragma unroll
;       for (int r = 0; r < 16; ++r) {
;         float pa, pb;
;         if (MODE == 1) {
;           if (FAST) { pa = __builtin_amdgcn_exp2f(s0[r]); pb = __builtin_amdgcn_exp2f(s1[r]); }
;           else { pa = __builtin_amdgcn_exp2f(s0[r] - mn); pb = __builtin_amdgcn_exp2f(s1[r] - mn); }
;         }
;         else { pa = __builtin_amdgcn_exp2f(s0[r] - mn); pb = __builtin_amdgcn_exp2f(s1[r] - mn); }
;         s0[r] = pa; s1[r] = pb; ls += pa + pb;
;       }
;       l[nq] += ls;
; #pragma unroll
;       for (int ks = 0; ks < 4; ++ks) {
;         uint4 t4;
;         const int rb = 8 * (ks & 1);
;         if (ks < 2) { t4.x = pack2(s0[rb], s0[rb + 1]); t4.y = pack2(s0[rb + 2], s0[rb + 3]); t4.z = pack2(s0[rb + 4], s0[rb + 5]); t4.w = pack2(s0[rb + 6], s0[rb + 7]); }
;         else { t4.x = pack2(s1[rb], s1[rb + 1]); t4.y = pack2(s1[rb + 2], s1[rb + 3]); t4.z = pack2(s1[rb + 4], s1[rb + 5]); t4.w = pack2(s1[rb + 6], s1[rb + 7]); }
;         pf[nq][ks] = __builtin_bit_cast(bf16x8, t4);
;       }
.LBB0_441:
	s_lshl_b32 s9, s8, 14
	v_or_b32_e32 v70, s9, v183
	ds_read_b128 v[66:69], v70
	ds_read_b128 v[82:85], v70 offset:4096
	v_or_b32_e32 v180, s9, v184
	ds_read_b128 v[176:179], v180
	ds_read_b128 v[188:191], v180 offset:4096
	v_or_b32_e32 v180, s9, v186
	s_waitcnt lgkmcnt(0)
	v_mfma_f32_32x32x16_bf16 v[98:113], v[66:69], v[130:133], 0
	v_mfma_f32_32x32x16_bf16 v[114:129], v[82:85], v[130:133], 0
	v_mfma_f32_32x32x16_bf16 v[66:81], v[66:69], v[146:149], 0
	v_mfma_f32_32x32x16_bf16 v[82:97], v[82:85], v[146:149], 0
	v_mfma_f32_32x32x16_bf16 v[98:113], v[176:179], v[134:137], v[98:113]
	v_mfma_f32_32x32x16_bf16 v[114:129], v[188:191], v[134:137], v[114:129]
	v_mfma_f32_32x32x16_bf16 v[66:81], v[176:179], v[150:153], v[66:81]
	v_mfma_f32_32x32x16_bf16 v[82:97], v[188:191], v[150:153], v[82:97]
	ds_read_b128 v[176:179], v180
	ds_read_b128 v[188:191], v180 offset:4096
	v_or_b32_e32 v180, s9, v187
	s_add_i32 s98, s7, 4
	s_min_i32 s98, s98, s6
	s_cmp_gt_i32 s8, 1
	s_cselect_b32 s99, -2, 4
	s_add_i32 s99, s99, s8
	s_lshl_b32 s99, s99, 14
	s_add_i32 s99, s4, s99
	v_mad_i64_i32 v[250:251], s[100:101], s98, v237, v[172:173]
	s_mov_b32 m0, s99
	s_nop 0
	global_load_lds_dwordx4 v[250:251], off
	v_mad_i64_i32 v[250:251], s[100:101], s98, v237, v[174:175]
	s_add_i32 m0, s99, 0x2000
	s_nop 0
	global_load_lds_dwordx4 v[250:251], off
	s_waitcnt lgkmcnt(0)
	v_mfma_f32_32x32x16_bf16 v[98:113], v[176:179], v[138:141], v[98:113]
	v_mfma_f32_32x32x16_bf16 v[114:129], v[188:191], v[138:141], v[114:129]
	v_mfma_f32_32x32x16_bf16 v[66:81], v[176:179], v[154:157], v[66:81]
	v_mfma_f32_32x32x16_bf16 v[82:97], v[188:191], v[154:157], v[82:97]
	ds_read_b128 v[176:179], v180
	ds_read_b128 v[188:191], v180 offset:4096
	s_waitcnt lgkmcnt(0)
	v_mfma_f32_32x32x16_bf16 v[98:113], v[176:179], v[142:145], v[98:113]
	v_mfma_f32_32x32x16_bf16 v[114:129], v[188:191], v[142:145], v[114:129]
	s_nop 10
	v_exp_f32_e32 v193, v100
	v_exp_f32_e32 v195, v101
	v_exp_f32_e32 v197, v102
	v_exp_f32_e32 v199, v103
	v_exp_f32_e32 v201, v104
	v_exp_f32_e32 v205, v105
	v_exp_f32_e32 v207, v106
	v_mfma_f32_32x32x16_bf16 v[66:81], v[176:179], v[158:161], v[66:81]
	v_exp_f32_e32 v177, v114
	v_exp_f32_e32 v115, v115
	v_exp_f32_e32 v179, v116
	v_exp_f32_e32 v117, v117
	v_exp_f32_e32 v181, v118
	v_exp_f32_e32 v119, v119
	v_exp_f32_e32 v203, v120
	v_mfma_f32_32x32x16_bf16 v[82:97], v[188:191], v[158:161], v[82:97]
	v_exp_f32_e32 v189, v98
	s_nop 2
	v_exp_f32_e32 v188, v66
	v_exp_f32_e32 v191, v99
	v_exp_f32_e32 v190, v67
	v_exp_f32_e32 v192, v68
	v_exp_f32_e32 v194, v69
	v_exp_f32_e32 v196, v70
	s_nop 1
	v_exp_f32_e32 v176, v82
	v_exp_f32_e32 v114, v83
	v_exp_f32_e32 v178, v84
	v_exp_f32_e32 v116, v85
	v_exp_f32_e32 v180, v86
	v_pk_add_f32 v[66:67], v[188:189], v[176:177]
	v_pk_add_f32 v[68:69], v[190:191], v[114:115]
	v_pk_add_f32 v[66:67], v[66:67], 0 op_sel_hi:[1,0]
	v_exp_f32_e32 v198, v71
	v_exp_f32_e32 v118, v87
	v_pk_add_f32 v[66:67], v[68:69], v[66:67]
	v_pk_add_f32 v[68:69], v[192:193], v[178:179]
	v_exp_f32_e32 v200, v72
	v_exp_f32_e32 v202, v88
	v_exp_f32_e32 v121, v121
	v_pk_add_f32 v[66:67], v[68:69], v[66:67]
	v_pk_add_f32 v[68:69], v[194:195], v[116:117]
	v_exp_f32_e32 v204, v73
	v_exp_f32_e32 v120, v89
	v_exp_f32_e32 v209, v122
	v_pk_add_f32 v[66:67], v[68:69], v[66:67]
	v_pk_add_f32 v[68:69], v[196:197], v[180:181]
	v_exp_f32_e32 v206, v74
	v_exp_f32_e32 v208, v90
	v_exp_f32_e32 v211, v107
	v_exp_f32_e32 v123, v123
	v_pk_add_f32 v[66:67], v[68:69], v[66:67]
	v_pk_add_f32 v[68:69], v[198:199], v[118:119]
	v_exp_f32_e32 v210, v75
	v_exp_f32_e32 v122, v91
	v_exp_f32_e32 v213, v108
	v_exp_f32_e32 v215, v124
	v_exp_f32_e32 v212, v76
	v_exp_f32_e32 v214, v92
	v_pk_add_f32 v[66:67], v[68:69], v[66:67]
	v_pk_add_f32 v[68:69], v[200:201], v[202:203]
	v_exp_f32_e32 v217, v109
	v_exp_f32_e32 v125, v125
	v_exp_f32_e32 v216, v77
	v_exp_f32_e32 v124, v93
	v_pk_add_f32 v[66:67], v[68:69], v[66:67]
	v_pk_add_f32 v[68:69], v[204:205], v[120:121]
	v_exp_f32_e32 v219, v110
	v_exp_f32_e32 v221, v126
	v_exp_f32_e32 v218, v78
	v_exp_f32_e32 v220, v94
	v_pk_add_f32 v[66:67], v[68:69], v[66:67]
	v_pk_add_f32 v[68:69], v[206:207], v[208:209]
	v_exp_f32_e32 v227, v111
	v_exp_f32_e32 v127, v127
	v_exp_f32_e32 v226, v79
	v_exp_f32_e32 v126, v95
	v_pk_add_f32 v[66:67], v[68:69], v[66:67]
	v_pk_add_f32 v[68:69], v[210:211], v[122:123]
	v_exp_f32_e32 v229, v112
	v_exp_f32_e32 v243, v128
	v_exp_f32_e32 v228, v80
	v_exp_f32_e32 v242, v96
	v_pk_add_f32 v[66:67], v[68:69], v[66:67]
	v_pk_add_f32 v[68:69], v[212:213], v[214:215]
	v_exp_f32_e32 v245, v113
	v_exp_f32_e32 v129, v129
	v_exp_f32_e32 v244, v81
	v_exp_f32_e32 v128, v97
	v_pk_add_f32 v[66:67], v[68:69], v[66:67]
	v_pk_add_f32 v[68:69], v[216:217], v[124:125]
	v_cvt_pk_bf16_f32 v110, v189, v191
	v_pk_add_f32 v[66:67], v[68:69], v[66:67]
	v_pk_add_f32 v[68:69], v[218:219], v[220:221]
	v_cvt_pk_bf16_f32 v111, v193, v195
	v_pk_add_f32 v[66:67], v[68:69], v[66:67]
	v_pk_add_f32 v[68:69], v[226:227], v[126:127]
	v_cvt_pk_bf16_f32 v112, v197, v199
	v_pk_add_f32 v[66:67], v[68:69], v[66:67]
	v_pk_add_f32 v[68:69], v[228:229], v[242:243]
	v_cvt_pk_bf16_f32 v113, v201, v205
	v_pk_add_f32 v[66:67], v[68:69], v[66:67]
	v_pk_add_f32 v[68:69], v[244:245], v[128:129]
	v_cvt_pk_bf16_f32 v106, v207, v211
	v_cvt_pk_bf16_f32 v107, v213, v217
	v_cvt_pk_bf16_f32 v108, v219, v227
	v_cvt_pk_bf16_f32 v109, v229, v245
	v_cvt_pk_bf16_f32 v102, v177, v115
	v_cvt_pk_bf16_f32 v103, v179, v117
	v_cvt_pk_bf16_f32 v104, v181, v119
	v_cvt_pk_bf16_f32 v105, v203, v121
	v_cvt_pk_bf16_f32 v98, v209, v123
	v_cvt_pk_bf16_f32 v99, v215, v125
	v_cvt_pk_bf16_f32 v100, v221, v127
	v_cvt_pk_bf16_f32 v101, v243, v129
	v_pk_add_f32 v[82:83], v[68:69], v[66:67]
	v_cvt_pk_bf16_f32 v78, v188, v190
	v_cvt_pk_bf16_f32 v79, v192, v194
	v_cvt_pk_bf16_f32 v80, v196, v198
	v_cvt_pk_bf16_f32 v81, v200, v204
	v_cvt_pk_bf16_f32 v74, v206, v210
	v_cvt_pk_bf16_f32 v75, v212, v216
	v_cvt_pk_bf16_f32 v76, v218, v226
	v_cvt_pk_bf16_f32 v77, v228, v244
	v_cvt_pk_bf16_f32 v70, v176, v114
	v_cvt_pk_bf16_f32 v71, v178, v116
	v_cvt_pk_bf16_f32 v72, v180, v118
	v_cvt_pk_bf16_f32 v73, v202, v120
	v_cvt_pk_bf16_f32 v66, v208, v122
	v_cvt_pk_bf16_f32 v67, v214, v124
	v_cvt_pk_bf16_f32 v68, v220, v126
	v_cvt_pk_bf16_f32 v69, v242, v128

; __global__ void __launch_bounds__(512) fwd_megakernel(Params p) {
;   cg::grid_group grid = cg::this_grid();
;   __shared__ __attribute__((aligned(1024))) char lds[8 * HTB + 64 + 2048];
	.amdhsa_kernel _Z14fwd_megakernel6Params
		.amdhsa_group_segment_fixed_size 133184
		.amdhsa_private_segment_fixed_size 0
		.amdhsa_kernarg_size 432
		.amdhsa_user_sgpr_count 2
		.amdhsa_user_sgpr_dispatch_ptr 0
		.amdhsa_user_sgpr_queue_ptr 0
		.amdhsa_user_sgpr_kernarg_segment_ptr 1
		.amdhsa_user_sgpr_dispatch_id 0
		.amdhsa_user_sgpr_kernarg_preload_length 0
		.amdhsa_user_sgpr_kernarg_preload_offset 0
		.amdhsa_user_sgpr_private_segment_size 0
		.amdhsa_uses_dynamic_stack 0
		.amdhsa_enable_private_segment 0
		.amdhsa_system_sgpr_workgroup_id_x 1
		.amdhsa_system_sgpr_workgroup_id_y 0
		.amdhsa_system_sgpr_workgroup_id_z 0
		.amdhsa_system_sgpr_workgroup_info 0
		.amdhsa_system_vgpr_workitem_id 2
		.amdhsa_next_free_vgpr 256
		.amdhsa_next_free_sgpr 102
		.amdhsa_accum_offset 256
		.amdhsa_reserve_vcc 1
		.amdhsa_float_round_mode_32 0
		.amdhsa_float_round_mode_16_64 0
		.amdhsa_float_denorm_mode_32 3
		.amdhsa_float_denorm_mode_16_64 3
		.amdhsa_dx10_clamp 1
		.amdhsa_ieee_mode 1
		.amdhsa_fp16_overflow 0
		.amdhsa_tg_split 0
		.amdhsa_exception_fp_ieee_invalid_op 0
		.amdhsa_exception_fp_denorm_src 0
		.amdhsa_exception_fp_ieee_div_zero 0
		.amdhsa_exception_fp_ieee_overflow 0
		.amdhsa_exception_fp_ieee_underflow 0
		.amdhsa_exception_fp_ieee_inexact 0
		.amdhsa_exception_int_div_zero 0
	.end_amdhsa_kernel

; __global__ void __launch_bounds__(512) fwd_megakernel(Params p) {
;   cg::grid_group grid = cg::this_grid();
;   __shared__ __attribute__((aligned(1024))) char lds[8 * HTB + 64 + 2048];
amdhsa.kernels:
  - .agpr_count:     0
    .args:
      - .offset:         0
        .size:           176
        .value_kind:     by_value
      - .offset:         176
        .size:           4
        .value_kind:     hidden_block_count_x
      - .offset:         180
        .size:           4
        .value_kind:     hidden_block_count_y
      - .offset:         184
        .size:           4
        .value_kind:     hidden_block_count_z
      - .offset:         188
        .size:           2
        .value_kind:     hidden_group_size_x
      - .offset:         190
        .size:           2
        .value_kind:     hidden_group_size_y
      - .offset:         192
        .size:           2
        .value_kind:     hidden_group_size_z
      - .offset:         194
        .size:           2
        .value_kind:     hidden_remainder_x
      - .offset:         196
        .size:           2
        .value_kind:     hidden_remainder_y
      - .offset:         198
        .size:           2
        .value_kind:     hidden_remainder_z
      - .offset:         216
        .size:           8
        .value_kind:     hidden_global_offset_x
      - .offset:         224
        .size:           8
        .value_kind:     hidden_global_offset_y
      - .offset:         232
        .size:           8
        .value_kind:     hidden_global_offset_z
      - .offset:         240
        .size:           2
        .value_kind:     hidden_grid_dims
      - .offset:         264
        .size:           8
        .value_kind:     hidden_multigrid_sync_arg
    .group_segment_fixed_size: 133184
    .kernarg_segment_align: 8
    .kernarg_segment_size: 432
    .language:       OpenCL C
    .language_version:
      - 2
      - 0
    .max_flat_workgroup_size: 512
    .name:           _Z14fwd_megakernel6Params
    .private_segment_fixed_size: 0
    .sgpr_count:     108
    .sgpr_spill_count: 192
    .symbol:         _Z14fwd_megakernel6Params.kd
    .uniform_work_group_size: 1
    .uses_dynamic_stack: false
    .vgpr_count:     256
    .vgpr_spill_count: 0
    .wavefront_size: 64
